# mixer C: rel-pos-bias LDS lookups batched (16+8+8 per half) instead of 64 serialized read-wait pairs per unit
# speedup vs baseline: 1.0038x; 1.0038x over previous
; #define LAS __attribute__((address_space(3)))
; __device__ __forceinline__ void mixC_mfma(const bf16* P, const float* rpb  , bf16* MIX, LAS unsigned char* lds, int bid, int G, int tid) {
;     ...
;         const int r = rf + (wave >> 2), j = wave & 3;
;         int rs = r - 4; rs = rs < 0 ? 0 : rs; rs = rs > rows - 8 ? rows - 8 : rs;
;         const int kcol0 = j == 0 ? 0 : (j == 1 ? 8 : (j == 2 ? 24 : 32));
;         const int c = 16 * j + fr; int cs = c - 8; cs = cs < 0 ? 0 : cs; cs = cs > 48 ? 48 : cs;
;         const size_t qrow = (size_t)(s0 + r * 64 + c);
;         f32x4 S[16];
;         bf16x8 Kl[8][2];
; #pragma unroll
;         for (int kt = 8; kt < 16; ++kt) { const bf16* kp = P + (size_t)(s0 + (rs + (kt >> 1)) * 64 + kcol0 + 16 * (kt & 1) + fr) * DIN + C_KC + h * 64 + fq * 8;
;             Kl[kt - 8][0] = *(const bf16x8*)kp; Kl[kt - 8][1] = *(const bf16x8*)(kp + 32); }
; #pragma unroll
;         for (int kt = 0; kt < 8; ++kt) { f32x4 z = {0.f, 0.f, 0.f, 0.f};
;             z = __builtin_amdgcn_mfma_f32_16x16x32_bf16(Kn[kt][0], Qn0, z, 0, 0, 0);
;             S[kt] = __builtin_amdgcn_mfma_f32_16x16x32_bf16(Kn[kt][1], Qn1, z, 0, 0, 0); }
;         const int d0 = kcol0 + 4 * fq - cs;
;         const LAS float* rpl = rp + h * 512 + (rs - r + 7) * 31 + (kcol0 + 4 * fq - c + 15);
;         float m1 = -1e30f;
; #pragma unroll
;         for (int kt = 0; kt < 8; ++kt)
; #pragma unroll
;             for (int t = 0; t < 4; ++t) {
;                 const bool ok = (unsigned)(d0 + 16 * (kt & 1) + t) < 16u;
;                 const float sv = ok ? S[kt][t] * (0.125f * L2E) + rpl[(kt >> 1) * 31 + 16 * (kt & 1) + t] : -1e30f;
;                 S[kt][t] = sv; m1 = fmaxf(m1, sv);
;             }
.LBB0_358:
	s_add_i32 s90, s90, s12
	s_max_i32 s0, s90, 4
	s_add_i32 s0, s0, -4
	s_min_u32 s92, s0, s5
	v_or_b32_e32 v110, s89, v207
	s_lshl_b32 s5, s92, 6
	v_add_u32_e32 v162, s35, v110
	s_add_i32 s6, s5, 0x100
	s_lshl_b32 s80, s4, 6
	v_add_u32_e32 v110, s6, v162
	v_mov_b64_e32 v[170:171], s[74:75]
	s_ashr_i32 s81, s80, 31
	v_mad_i64_i32 v[110:111], s[0:1], v110, s79, v[170:171]
	s_lshl_b64 s[0:1], s[80:81], 1
	v_add_u32_e32 v172, 16, v162
	v_lshl_add_u64 v[110:111], v[110:111], 0, s[0:1]
	v_add_u32_e32 v118, s6, v172
	v_lshl_add_u64 v[110:111], v[110:111], 0, v[210:211]
	v_mad_i64_i32 v[118:119], s[6:7], v118, s79, v[170:171]
	s_add_i32 s8, s5, 0x140
	s_waitcnt vmcnt(15)
	v_mfma_f32_16x16x32_bf16 v[142:145], v[46:49], v[38:41], 0
	v_lshl_add_u64 v[114:115], v[110:111], 0, s[22:23]
	v_add_co_u32_e32 v110, vcc, s88, v110
	v_lshl_add_u64 v[118:119], v[118:119], 0, s[0:1]
	v_add_u32_e32 v126, s8, v162
	v_addc_co_u32_e32 v111, vcc, 0, v111, vcc
	v_lshl_add_u64 v[118:119], v[118:119], 0, v[210:211]
	v_mad_i64_i32 v[126:127], s[6:7], v126, s79, v[170:171]
	v_lshl_add_u64 v[122:123], v[118:119], 0, s[22:23]
	v_add_co_u32_e32 v118, vcc, s88, v118
	v_lshl_add_u64 v[126:127], v[126:127], 0, s[0:1]
	v_add_u32_e32 v134, s8, v172
	s_add_i32 s8, s5, 0x180
	v_addc_co_u32_e32 v119, vcc, 0, v119, vcc
	v_lshl_add_u64 v[126:127], v[126:127], 0, v[210:211]
	v_mad_i64_i32 v[134:135], s[6:7], v134, s79, v[170:171]
	s_waitcnt vmcnt(14)
	v_mfma_f32_16x16x32_bf16 v[202:205], v[50:53], v[42:45], v[142:145]
	v_lshl_add_u64 v[130:131], v[126:127], 0, s[22:23]
	v_add_co_u32_e32 v126, vcc, s88, v126
	s_nop 0
	v_add_u32_e32 v142, s8, v162
	v_lshl_add_u64 v[134:135], v[134:135], 0, s[0:1]
	v_mad_i64_i32 v[146:147], s[6:7], v142, s79, v[170:171]
	s_waitcnt vmcnt(13)
	v_mfma_f32_16x16x32_bf16 v[142:145], v[54:57], v[38:41], 0
	v_addc_co_u32_e32 v127, vcc, 0, v127, vcc
	v_lshl_add_u64 v[134:135], v[134:135], 0, v[210:211]
	v_lshl_add_u64 v[136:137], v[134:135], 0, s[22:23]
	v_add_co_u32_e32 v134, vcc, s88, v134
	v_lshl_add_u64 v[146:147], v[146:147], 0, s[0:1]
	s_nop 0
	v_addc_co_u32_e32 v135, vcc, 0, v135, vcc
	v_lshl_add_u64 v[146:147], v[146:147], 0, v[210:211]
	s_waitcnt vmcnt(12)
	v_mfma_f32_16x16x32_bf16 v[198:201], v[58:61], v[42:45], v[142:145]
	v_lshl_add_u64 v[150:151], v[146:147], 0, s[22:23]
	global_load_dwordx4 v[110:113], v[110:111], off
	s_nop 0
	global_load_dwordx4 v[114:117], v[114:115], off offset:64
	v_add_co_u32_e32 v142, vcc, s88, v146
	global_load_dwordx4 v[118:121], v[118:119], off
	s_nop 0
	global_load_dwordx4 v[122:125], v[122:123], off offset:64
	v_addc_co_u32_e32 v143, vcc, 0, v147, vcc
	global_load_dwordx4 v[126:129], v[126:127], off
	s_nop 0
	global_load_dwordx4 v[130:133], v[130:131], off offset:64
	s_nop 0
	global_load_dwordx4 v[138:141], v[134:135], off
	s_nop 0
	global_load_dwordx4 v[134:137], v[136:137], off offset:64
	s_nop 0
	global_load_dwordx4 v[146:149], v[142:143], off
	s_nop 0
	global_load_dwordx4 v[142:145], v[150:151], off offset:64
	s_waitcnt vmcnt(21)
	v_mfma_f32_16x16x32_bf16 v[150:153], v[62:65], v[38:41], 0
	v_add_u32_e32 v154, s8, v172
	v_mad_i64_i32 v[154:155], s[6:7], v154, s79, v[170:171]
	s_waitcnt vmcnt(20)
	v_mfma_f32_16x16x32_bf16 v[194:197], v[66:69], v[42:45], v[150:153]
	s_addk_i32 s5, 0x1c0
	v_add_u32_e32 v162, s5, v162
	v_mad_i64_i32 v[162:163], s[6:7], v162, s79, v[170:171]
	s_nop 0
	v_lshl_add_u64 v[150:151], v[154:155], 0, s[0:1]
	v_lshl_add_u64 v[154:155], v[150:151], 0, v[210:211]
	s_waitcnt vmcnt(19)
	v_mfma_f32_16x16x32_bf16 v[150:153], v[70:73], v[38:41], 0
	v_lshl_add_u64 v[158:159], v[154:155], 0, s[22:23]
	v_add_co_u32_e32 v154, vcc, s88, v154
	s_waitcnt vmcnt(15)
	v_mfma_f32_16x16x32_bf16 v[166:169], v[86:89], v[38:41], 0
	v_addc_co_u32_e32 v155, vcc, 0, v155, vcc
	v_add_u32_e32 v217, s35, v212
	v_mfma_f32_16x16x32_bf16 v[190:193], v[74:77], v[42:45], v[150:153]
	global_load_dwordx4 v[154:157], v[154:155], off
	s_nop 1
	global_load_dwordx4 v[150:153], v[158:159], off offset:64
	v_sub_u32_e32 v215, v217, v209
	v_sub_u32_e32 v217, v217, v1
	v_mfma_f32_16x16x32_bf16 v[158:161], v[82:85], v[38:41], 0
	s_waitcnt vmcnt(16)
	v_mfma_f32_16x16x32_bf16 v[182:185], v[90:93], v[42:45], v[166:169]
	s_nop 2
	v_add_u32_e32 v166, s5, v172
	v_mfma_f32_16x16x32_bf16 v[186:189], v[78:81], v[42:45], v[158:161]
	v_mad_i64_i32 v[170:171], s[6:7], v166, s79, v[170:171]
	v_lshl_add_u64 v[170:171], v[170:171], 0, s[0:1]
	s_nop 0
	v_lshl_add_u64 v[158:159], v[162:163], 0, s[0:1]
	s_waitcnt vmcnt(15)
	v_mfma_f32_16x16x32_bf16 v[166:169], v[94:97], v[38:41], 0
	v_lshl_add_u64 v[158:159], v[158:159], 0, v[210:211]
	v_lshl_add_u64 v[160:161], v[158:159], 0, s[22:23]
	v_add_co_u32_e32 v158, vcc, s88, v158
	v_lshl_add_u64 v[170:171], v[170:171], 0, v[210:211]
	s_nop 0
	v_addc_co_u32_e32 v159, vcc, 0, v159, vcc
	s_waitcnt vmcnt(14)
	v_mfma_f32_16x16x32_bf16 v[178:181], v[98:101], v[42:45], v[166:169]
	global_load_dwordx4 v[162:165], v[158:159], off
	s_nop 0
	global_load_dwordx4 v[158:161], v[160:161], off offset:64
	v_add_co_u32_e32 v166, vcc, s88, v170
	v_lshl_add_u64 v[230:231], v[170:171], 0, s[22:23]
	s_nop 0
	v_addc_co_u32_e32 v167, vcc, 0, v171, vcc
	global_load_dwordx4 v[170:173], v[166:167], off
	s_nop 0
	global_load_dwordx4 v[166:169], v[230:231], off offset:64
	s_waitcnt vmcnt(17)
	v_mfma_f32_16x16x32_bf16 v[174:177], v[102:105], v[38:41], 0
	s_lshl_b32 s0, s4, 11
	s_sub_i32 s1, s92, s90
	s_add_i32 s0, s0, 0
	s_waitcnt vmcnt(16)
	v_mfma_f32_16x16x32_bf16 v[174:177], v[106:109], v[42:45], v[174:177]
	s_mulk_i32 s1, 0x7c
	s_add_i32 s0, s0, s1
	v_add_u32_e32 v230, 8, v215
	s_add_i32 s0, s0, 0x16800
	v_lshl_add_u32 v231, v217, 2, s0
	ds_read_b32 v46, v231 offset:928
	ds_read_b32 v47, v231 offset:932
	ds_read_b32 v48, v231 offset:936
	ds_read_b32 v49, v231 offset:940
	ds_read_b32 v50, v231 offset:992
	ds_read_b32 v51, v231 offset:996
	ds_read_b32 v52, v231 offset:1000
	ds_read_b32 v53, v231 offset:1004
	ds_read_b32 v54, v231 offset:1052
	ds_read_b32 v55, v231 offset:1056
	ds_read_b32 v56, v231 offset:1060
	ds_read_b32 v57, v231 offset:1064
	ds_read_b32 v58, v231 offset:1116
	ds_read_b32 v59, v231 offset:1120
	ds_read_b32 v60, v231 offset:1124
	ds_read_b32 v61, v231 offset:1128
	v_cmp_gt_u32_e64 s[0:1], 16, v230
	v_mov_b32_e32 v217, 0xf149f2ca
	v_mov_b32_e32 v230, 0xf149f2ca
	s_and_saveexec_b64 s[4:5], s[0:1]
	s_cbranch_execz .LBB0_360
	s_waitcnt lgkmcnt(0)
	v_fmamk_f32 v230, v202, 0x3e38aa3b, v46
; __device__ __forceinline__ void mixC_mfma(const bf16* P, const float* rpb  , bf16* MIX, LAS unsigned char* lds, int bid, int G, int tid) {
;     ...
; #pragma unroll
;         for (int kt = 0; kt < 8; ++kt)
; #pragma unroll
;             for (int t = 0; t < 4; ++t) {
;                 const bool ok = (unsigned)(d0 + 16 * (kt & 1) + t) < 16u;
;                 const float sv = ok ? S[kt][t] * (0.125f * L2E) + rpl[(kt >> 1) * 31 + 16 * (kt & 1) + t] : -1e30f;
;                 S[kt][t] = sv; m1 = fmaxf(m1, sv);
;             }
.LBB0_360:
	s_or_b64 exec, exec, s[4:5]
	v_add_u32_e32 v202, 9, v215
	v_cmp_gt_u32_e64 s[4:5], 16, v202
	s_and_saveexec_b64 s[6:7], s[4:5]
	s_cbranch_execz .LBB0_362
	s_waitcnt lgkmcnt(0)
	v_fmamk_f32 v217, v203, 0x3e38aa3b, v47
.LBB0_362:
	s_or_b64 exec, exec, s[6:7]
	v_add_u32_e32 v202, 10, v215
	v_cmp_gt_u32_e64 s[6:7], 16, v202
	v_mov_b32_e32 v202, 0xf149f2ca
	v_mov_b32_e32 v203, 0xf149f2ca
	s_and_saveexec_b64 s[8:9], s[6:7]
	s_cbranch_execz .LBB0_364
	s_waitcnt lgkmcnt(0)
	v_fmamk_f32 v203, v204, 0x3e38aa3b, v48
.LBB0_364:
	s_or_b64 exec, exec, s[8:9]
	v_add_u32_e32 v204, 11, v215
	v_cmp_gt_u32_e64 s[8:9], 16, v204
	s_and_saveexec_b64 s[10:11], s[8:9]
	s_cbranch_execz .LBB0_366
	s_waitcnt lgkmcnt(0)
	v_fmamk_f32 v202, v205, 0x3e38aa3b, v49
.LBB0_366:
	s_or_b64 exec, exec, s[10:11]
	v_add_u32_e32 v204, 24, v215
	v_cmp_gt_u32_e64 s[10:11], 16, v204
	v_mov_b32_e32 v204, 0xf149f2ca
	v_mov_b32_e32 v205, 0xf149f2ca
	s_and_saveexec_b64 s[14:15], s[10:11]
	s_cbranch_execz .LBB0_368
	s_waitcnt lgkmcnt(0)
	v_fmamk_f32 v205, v198, 0x3e38aa3b, v50
.LBB0_368:
	s_or_b64 exec, exec, s[14:15]
	v_add_u32_e32 v198, 25, v215
	v_cmp_gt_u32_e64 s[14:15], 16, v198
	s_and_saveexec_b64 s[16:17], s[14:15]
	s_cbranch_execz .LBB0_370
	s_waitcnt lgkmcnt(0)
	v_fmamk_f32 v204, v199, 0x3e38aa3b, v51
.LBB0_370:
	s_or_b64 exec, exec, s[16:17]
	v_add_u32_e32 v198, 26, v215
	v_cmp_gt_u32_e64 s[16:17], 16, v198
	v_mov_b32_e32 v198, 0xf149f2ca
	v_mov_b32_e32 v199, 0xf149f2ca
	s_and_saveexec_b64 s[18:19], s[16:17]
	s_cbranch_execz .LBB0_372
	s_waitcnt lgkmcnt(0)
	v_fmamk_f32 v199, v200, 0x3e38aa3b, v52
.LBB0_372:
	s_or_b64 exec, exec, s[18:19]
	v_add_u32_e32 v200, 27, v215
	v_cmp_gt_u32_e64 s[18:19], 16, v200
	s_and_saveexec_b64 s[82:83], s[18:19]
	s_cbranch_execz .LBB0_374
	s_waitcnt lgkmcnt(0)
	v_fmamk_f32 v198, v201, 0x3e38aa3b, v53
.LBB0_374:
	s_or_b64 exec, exec, s[82:83]
	s_waitcnt lgkmcnt(0)
	ds_read_b32 v46, v231 offset:1176
	ds_read_b32 v47, v231 offset:1180
	ds_read_b32 v48, v231 offset:1184
	ds_read_b32 v49, v231 offset:1188
	ds_read_b32 v50, v231 offset:1240
	ds_read_b32 v51, v231 offset:1244
	ds_read_b32 v52, v231 offset:1248
	ds_read_b32 v53, v231 offset:1252
	v_mov_b32_e32 v200, 0xf149f2ca
	v_mov_b32_e32 v201, 0xf149f2ca
	s_and_saveexec_b64 s[82:83], s[0:1]
	s_cbranch_execz .LBB0_376
	s_waitcnt lgkmcnt(8)
	v_fmamk_f32 v201, v194, 0x3e38aa3b, v54
.LBB0_376:
	s_or_b64 exec, exec, s[82:83]
	s_and_saveexec_b64 s[82:83], s[4:5]
	s_cbranch_execz .LBB0_378
	s_waitcnt lgkmcnt(8)
	v_fmamk_f32 v200, v195, 0x3e38aa3b, v55
.LBB0_378:
	s_or_b64 exec, exec, s[82:83]
	v_mov_b32_e32 v194, 0xf149f2ca
	v_mov_b32_e32 v195, 0xf149f2ca
	s_and_saveexec_b64 s[82:83], s[6:7]
	s_cbranch_execz .LBB0_380
	s_waitcnt lgkmcnt(8)
	v_fmamk_f32 v195, v196, 0x3e38aa3b, v56
.LBB0_380:
	s_or_b64 exec, exec, s[82:83]
	s_and_saveexec_b64 s[82:83], s[8:9]
	s_cbranch_execz .LBB0_382
	s_waitcnt lgkmcnt(8)
	v_fmamk_f32 v194, v197, 0x3e38aa3b, v57
.LBB0_382:
	s_or_b64 exec, exec, s[82:83]
	v_mov_b32_e32 v196, 0xf149f2ca
	v_mov_b32_e32 v197, 0xf149f2ca
	s_and_saveexec_b64 s[82:83], s[10:11]
	s_cbranch_execz .LBB0_384
	s_waitcnt lgkmcnt(8)
	v_fmamk_f32 v197, v190, 0x3e38aa3b, v58
.LBB0_384:
	s_or_b64 exec, exec, s[82:83]
	s_and_saveexec_b64 s[82:83], s[14:15]
	s_cbranch_execz .LBB0_386
	s_waitcnt lgkmcnt(8)
	v_fmamk_f32 v196, v191, 0x3e38aa3b, v59
.LBB0_386:
	s_or_b64 exec, exec, s[82:83]
	v_mov_b32_e32 v190, 0xf149f2ca
	v_mov_b32_e32 v191, 0xf149f2ca
	s_and_saveexec_b64 s[82:83], s[16:17]
	s_cbranch_execz .LBB0_388
	s_waitcnt lgkmcnt(8)
	v_fmamk_f32 v191, v192, 0x3e38aa3b, v60
.LBB0_388:
	s_or_b64 exec, exec, s[82:83]
	s_and_saveexec_b64 s[82:83], s[18:19]
	s_cbranch_execz .LBB0_390
	s_waitcnt lgkmcnt(8)
	v_fmamk_f32 v190, v193, 0x3e38aa3b, v61
.LBB0_390:
	s_or_b64 exec, exec, s[82:83]
	s_waitcnt lgkmcnt(0)
	ds_read_b32 v54, v231 offset:1300
	ds_read_b32 v55, v231 offset:1304
	ds_read_b32 v56, v231 offset:1308
	ds_read_b32 v57, v231 offset:1312
	ds_read_b32 v58, v231 offset:1364
	ds_read_b32 v59, v231 offset:1368
	ds_read_b32 v60, v231 offset:1372
	ds_read_b32 v61, v231 offset:1376
	v_mov_b32_e32 v192, 0xf149f2ca
	v_mov_b32_e32 v193, 0xf149f2ca
	s_and_saveexec_b64 s[82:83], s[0:1]
	s_cbranch_execz .LBB0_392
	s_waitcnt lgkmcnt(8)
	v_fmamk_f32 v193, v186, 0x3e38aa3b, v46
.LBB0_392:
	s_or_b64 exec, exec, s[82:83]
	s_and_saveexec_b64 s[82:83], s[4:5]
	s_cbranch_execz .LBB0_394
	s_waitcnt lgkmcnt(8)
	v_fmamk_f32 v192, v187, 0x3e38aa3b, v47
.LBB0_394:
	s_or_b64 exec, exec, s[82:83]
	v_mov_b32_e32 v186, 0xf149f2ca
	v_mov_b32_e32 v187, 0xf149f2ca
	s_and_saveexec_b64 s[82:83], s[6:7]
	s_cbranch_execz .LBB0_396
	s_waitcnt lgkmcnt(8)
	v_fmamk_f32 v187, v188, 0x3e38aa3b, v48
.LBB0_396:
	s_or_b64 exec, exec, s[82:83]
	s_and_saveexec_b64 s[82:83], s[8:9]
	s_cbranch_execz .LBB0_398
	s_waitcnt lgkmcnt(8)
	v_fmamk_f32 v186, v189, 0x3e38aa3b, v49
.LBB0_398:
	s_or_b64 exec, exec, s[82:83]
	v_mov_b32_e32 v188, 0xf149f2ca
	v_mov_b32_e32 v189, 0xf149f2ca
	s_and_saveexec_b64 s[82:83], s[10:11]
	s_cbranch_execz .LBB0_400
	s_waitcnt lgkmcnt(8)
	v_fmamk_f32 v189, v182, 0x3e38aa3b, v50
; __device__ __forceinline__ void mixC_mfma(const bf16* P, const float* rpb  , bf16* MIX, LAS unsigned char* lds, int bid, int G, int tid) {
;     ...
;                 const bool ok = (unsigned)(d0 + 16 * (kt & 1) + t) < 16u;
;                 const float sv = ok ? S[kt][t] * (0.125f * L2E) + rpl[(kt >> 1) * 31 + 16 * (kt & 1) + t] : -1e30f;
;                 S[kt][t] = sv; m1 = fmaxf(m1, sv);
;             }
;         m1 = fmaxf(m1, __shfl_xor(m1, 16)); m1 = fmaxf(m1, __shfl_xor(m1, 32));
;         float l1 = 0.f;
; #pragma unroll
;         for (int kt = 0; kt < 8; ++kt)
; #pragma unroll
;             for (int t = 0; t < 4; ++t) { const float p = __builtin_amdgcn_exp2f(S[kt][t] - m1); S[kt][t] = p; l1 += p; }
; #pragma unroll
;         for (int kt = 8; kt < 16; ++kt) { f32x4 z = {0.f, 0.f, 0.f, 0.f};
;             z = __builtin_amdgcn_mfma_f32_16x16x32_bf16(Kl[kt - 8][0], Qn0, z, 0, 0, 0);
;             S[kt] = __builtin_amdgcn_mfma_f32_16x16x32_bf16(Kl[kt - 8][1], Qn1, z, 0, 0, 0); }
;         asm volatile("" ::: "memory");
;         if (un + G < NU) c_prefetch(P, un + G, tid, wave, fr, fq, vpre, Qn0, Qn1, Kn);
.LBB0_400:
	s_or_b64 exec, exec, s[82:83]
	s_and_saveexec_b64 s[82:83], s[14:15]
	s_cbranch_execz .LBB0_402
	s_waitcnt lgkmcnt(8)
	v_fmamk_f32 v188, v183, 0x3e38aa3b, v51
.LBB0_402:
	s_or_b64 exec, exec, s[82:83]
	v_mov_b32_e32 v182, 0xf149f2ca
	v_mov_b32_e32 v183, 0xf149f2ca
	s_and_saveexec_b64 s[82:83], s[16:17]
	s_cbranch_execz .LBB0_404
	s_waitcnt lgkmcnt(8)
	v_fmamk_f32 v183, v184, 0x3e38aa3b, v52
.LBB0_404:
	s_or_b64 exec, exec, s[82:83]
	s_and_saveexec_b64 s[82:83], s[18:19]
	s_cbranch_execz .LBB0_406
	s_waitcnt lgkmcnt(8)
	v_fmamk_f32 v182, v185, 0x3e38aa3b, v53
.LBB0_406:
	s_or_b64 exec, exec, s[82:83]
	v_mov_b32_e32 v184, 0xf149f2ca
	v_mov_b32_e32 v185, 0xf149f2ca
	s_and_saveexec_b64 s[82:83], s[0:1]
	s_cbranch_execz .LBB0_408
	s_waitcnt lgkmcnt(0)
	v_fmamk_f32 v185, v178, 0x3e38aa3b, v54
.LBB0_408:
	s_or_b64 exec, exec, s[82:83]
	s_and_saveexec_b64 s[82:83], s[4:5]
	s_cbranch_execz .LBB0_410
	s_waitcnt lgkmcnt(0)
	v_fmamk_f32 v184, v179, 0x3e38aa3b, v55
.LBB0_410:
	s_or_b64 exec, exec, s[82:83]
	v_mov_b32_e32 v232, 0xf149f2ca
	v_mov_b32_e32 v233, 0xf149f2ca
	s_and_saveexec_b64 s[82:83], s[6:7]
	s_cbranch_execz .LBB0_412
	s_waitcnt lgkmcnt(0)
	v_fmamk_f32 v233, v180, 0x3e38aa3b, v56
.LBB0_412:
	s_or_b64 exec, exec, s[82:83]
	s_and_saveexec_b64 s[82:83], s[8:9]
	s_cbranch_execz .LBB0_414
	s_waitcnt lgkmcnt(0)
	v_fmamk_f32 v232, v181, 0x3e38aa3b, v57
.LBB0_414:
	s_or_b64 exec, exec, s[82:83]
	v_mov_b32_e32 v234, 0xf149f2ca
	v_mov_b32_e32 v235, 0xf149f2ca
	s_and_saveexec_b64 s[82:83], s[10:11]
	s_cbranch_execz .LBB0_416
	s_waitcnt lgkmcnt(0)
	v_fmamk_f32 v235, v174, 0x3e38aa3b, v58
.LBB0_416:
	s_or_b64 exec, exec, s[82:83]
	s_and_saveexec_b64 s[82:83], s[14:15]
	s_cbranch_execz .LBB0_418
	s_waitcnt lgkmcnt(0)
	v_fmamk_f32 v234, v175, 0x3e38aa3b, v59
.LBB0_418:
	s_or_b64 exec, exec, s[82:83]
	v_mov_b32_e32 v236, 0xf149f2ca
	v_mov_b32_e32 v237, 0xf149f2ca
	s_and_saveexec_b64 s[82:83], s[16:17]
	s_cbranch_execz .LBB0_420
	s_waitcnt lgkmcnt(0)
	v_fmamk_f32 v237, v176, 0x3e38aa3b, v60
.LBB0_420:
	s_or_b64 exec, exec, s[82:83]
	s_and_saveexec_b64 s[82:83], s[18:19]
	s_cbranch_execz .LBB0_422
	s_waitcnt lgkmcnt(0)
	v_fmamk_f32 v236, v177, 0x3e38aa3b, v61
.LBB0_422:
	s_or_b64 exec, exec, s[82:83]
	s_waitcnt vmcnt(15)
	v_mfma_f32_16x16x32_bf16 v[110:113], v[110:113], v[38:41], 0
	s_mov_b32 s24, 0xf149f2ca
	s_add_i32 s3, s3, s68
	s_waitcnt vmcnt(14)
	v_mfma_f32_16x16x32_bf16 v[178:181], v[114:117], v[42:45], v[110:113]
	v_max3_f32 v114, v230, s24, v217
	s_cmpk_gt_i32 s3, 0x8ff
	s_cselect_b64 s[82:83], -1, 0
	s_waitcnt vmcnt(13)
	v_mfma_f32_16x16x32_bf16 v[110:113], v[118:121], v[38:41], 0
	s_and_b64 vcc, exec, s[82:83]
	s_waitcnt vmcnt(12)
	v_mfma_f32_16x16x32_bf16 v[174:177], v[122:125], v[42:45], v[110:113]
	s_waitcnt vmcnt(11)
	v_mfma_f32_16x16x32_bf16 v[110:113], v[126:129], v[38:41], 0
	s_waitcnt vmcnt(10)
	v_mfma_f32_16x16x32_bf16 v[130:133], v[130:133], v[42:45], v[110:113]
	s_waitcnt vmcnt(9)
	v_mfma_f32_16x16x32_bf16 v[110:113], v[138:141], v[38:41], 0
	s_waitcnt vmcnt(8)
	v_mfma_f32_16x16x32_bf16 v[126:129], v[134:137], v[42:45], v[110:113]
	s_nop 5
	v_max3_f32 v110, v114, v203, v202
	v_max3_f32 v110, v110, v205, v204
	v_max3_f32 v114, v110, v199, v198
	s_waitcnt vmcnt(7)
	v_mfma_f32_16x16x32_bf16 v[110:113], v[146:149], v[38:41], 0
	v_max3_f32 v114, v114, v201, v200
	v_max3_f32 v114, v114, v195, v194
	v_max3_f32 v114, v114, v197, v196
	s_waitcnt vmcnt(6)
	v_mfma_f32_16x16x32_bf16 v[122:125], v[142:145], v[42:45], v[110:113]
	s_nop 2
	v_max3_f32 v110, v114, v191, v190
	v_max3_f32 v110, v110, v193, v192
	v_max3_f32 v114, v110, v187, v186
	s_waitcnt vmcnt(5)
	v_mfma_f32_16x16x32_bf16 v[110:113], v[154:157], v[38:41], 0
	v_max3_f32 v114, v114, v189, v188
	v_max3_f32 v114, v114, v183, v182
	v_max3_f32 v114, v114, v185, v184
	s_waitcnt vmcnt(4)
	v_mfma_f32_16x16x32_bf16 v[118:121], v[150:153], v[42:45], v[110:113]
	s_nop 2
	v_max3_f32 v110, v114, v233, v232
	v_max3_f32 v110, v110, v235, v234
	v_max3_f32 v114, v110, v237, v236
	ds_bpermute_b32 v115, v219, v114
	s_waitcnt vmcnt(3)
	v_mfma_f32_16x16x32_bf16 v[110:113], v[162:165], v[38:41], 0
	s_waitcnt lgkmcnt(0)
	v_max_f32_e32 v115, v115, v115
	v_max_f32_e32 v134, v114, v115
	s_waitcnt vmcnt(2)
	v_mfma_f32_16x16x32_bf16 v[114:117], v[158:161], v[42:45], v[110:113]
	ds_bpermute_b32 v135, v220, v134
	s_waitcnt vmcnt(1)
	v_mfma_f32_16x16x32_bf16 v[110:113], v[170:173], v[38:41], 0
	s_waitcnt vmcnt(0)
	v_mfma_f32_16x16x32_bf16 v[110:113], v[166:169], v[42:45], v[110:113]
	ds_read_b32 v239, v231 offset:1424
	ds_read_b32 v240, v231 offset:1428
	ds_read_b32 v241, v231 offset:1432
	ds_read_b32 v242, v231 offset:1436
	ds_read_b32 v243, v231 offset:1488
	ds_read_b32 v244, v231 offset:1492
	ds_read_b32 v245, v231 offset:1496
	ds_read_b32 v246, v231 offset:1500
	ds_read_b32 v247, v231 offset:1548
	ds_read_b32 v248, v231 offset:1552
	ds_read_b32 v249, v231 offset:1556
	ds_read_b32 v250, v231 offset:1560
	ds_read_b32 v251, v231 offset:1612
	ds_read_b32 v252, v231 offset:1616
	ds_read_b32 v253, v231 offset:1620
	ds_read_b32 v254, v231 offset:1624
	s_cbranch_vccz .LBB0_486
	v_mov_b32_e32 v138, 0xf149f2ca
	v_mov_b32_e32 v139, 0xf149f2ca
	s_and_saveexec_b64 s[84:85], s[0:1]
	s_cbranch_execnz .LBB0_492

; __device__ __forceinline__ void mixC_mfma(const bf16* P, const float* rpb  , bf16* MIX, LAS unsigned char* lds, int bid, int G, int tid) {
;     ...
; #pragma unroll
;         for (int kt = 8; kt < 16; ++kt)
; #pragma unroll
;             for (int t = 0; t < 4; ++t) {
;                 const bool ok = (unsigned)(d0 + 16 * (kt & 1) + t) < 16u;
;                 const float sv = ok ? S[kt][t] * (0.125f * L2E) + rpl[(kt >> 1) * 31 + 16 * (kt & 1) + t] : -1e30f;
;                 S[kt][t] = sv; mx = fmaxf(mx, sv);
;             }
.LBB0_425:
	s_waitcnt lgkmcnt(0)
	v_fmamk_f32 v138, v179, 0x3e38aa3b, v240
.LBB0_426:
	s_or_b64 exec, exec, s[84:85]
	v_mov_b32_e32 v143, 0xf149f2ca
	v_mov_b32_e32 v144, 0xf149f2ca
	s_and_saveexec_b64 s[84:85], s[6:7]
	s_cbranch_execz .LBB0_428
	s_waitcnt lgkmcnt(0)
	v_fmamk_f32 v144, v180, 0x3e38aa3b, v241
.LBB0_428:
	s_or_b64 exec, exec, s[84:85]
	s_and_saveexec_b64 s[84:85], s[8:9]
	s_cbranch_execz .LBB0_430
	s_waitcnt lgkmcnt(0)
	v_fmamk_f32 v143, v181, 0x3e38aa3b, v242
.LBB0_430:
	s_or_b64 exec, exec, s[84:85]
	v_mov_b32_e32 v145, 0xf149f2ca
	v_mov_b32_e32 v149, 0xf149f2ca
	s_and_saveexec_b64 s[84:85], s[10:11]
	s_cbranch_execz .LBB0_432
	s_waitcnt lgkmcnt(0)
	v_fmamk_f32 v149, v174, 0x3e38aa3b, v243
.LBB0_432:
	s_or_b64 exec, exec, s[84:85]
	s_and_saveexec_b64 s[84:85], s[14:15]
	s_cbranch_execz .LBB0_434
	s_waitcnt lgkmcnt(0)
	v_fmamk_f32 v145, v175, 0x3e38aa3b, v244
.LBB0_434:
	s_or_b64 exec, exec, s[84:85]
	v_mov_b32_e32 v151, 0xf149f2ca
	v_mov_b32_e32 v152, 0xf149f2ca
	s_and_saveexec_b64 s[84:85], s[16:17]
	s_cbranch_execz .LBB0_436
	s_waitcnt lgkmcnt(0)
	v_fmamk_f32 v152, v176, 0x3e38aa3b, v245
.LBB0_436:
	s_or_b64 exec, exec, s[84:85]
	s_and_saveexec_b64 s[84:85], s[18:19]
	s_cbranch_execz .LBB0_438
	s_waitcnt lgkmcnt(0)
	v_fmamk_f32 v151, v177, 0x3e38aa3b, v246
.LBB0_438:
	s_or_b64 exec, exec, s[84:85]
	s_waitcnt lgkmcnt(0)
	ds_read_b32 v239, v231 offset:1672
	ds_read_b32 v240, v231 offset:1676
	ds_read_b32 v241, v231 offset:1680
	ds_read_b32 v242, v231 offset:1684
	ds_read_b32 v243, v231 offset:1736
	ds_read_b32 v244, v231 offset:1740
	ds_read_b32 v245, v231 offset:1744
	ds_read_b32 v246, v231 offset:1748
	v_mov_b32_e32 v153, 0xf149f2ca
	v_mov_b32_e32 v154, 0xf149f2ca
	s_and_saveexec_b64 s[84:85], s[0:1]
	s_cbranch_execz .LBB0_440
	s_waitcnt lgkmcnt(8)
	v_fmamk_f32 v154, v130, 0x3e38aa3b, v247
.LBB0_440:
	s_or_b64 exec, exec, s[84:85]
	s_and_saveexec_b64 s[84:85], s[4:5]
	s_cbranch_execz .LBB0_442
	s_waitcnt lgkmcnt(8)
	v_fmamk_f32 v153, v131, 0x3e38aa3b, v248
.LBB0_442:
	s_or_b64 exec, exec, s[84:85]
	v_mov_b32_e32 v155, 0xf149f2ca
	v_mov_b32_e32 v156, 0xf149f2ca
	s_and_saveexec_b64 s[84:85], s[6:7]
	s_cbranch_execz .LBB0_444
	s_waitcnt lgkmcnt(8)
	v_fmamk_f32 v156, v132, 0x3e38aa3b, v249
.LBB0_444:
	s_or_b64 exec, exec, s[84:85]
	s_and_saveexec_b64 s[84:85], s[8:9]
	s_cbranch_execz .LBB0_446
	s_waitcnt lgkmcnt(8)
	v_fmamk_f32 v155, v133, 0x3e38aa3b, v250
.LBB0_446:
	s_or_b64 exec, exec, s[84:85]
	v_mov_b32_e32 v157, 0xf149f2ca
	v_mov_b32_e32 v158, 0xf149f2ca
	s_and_saveexec_b64 s[84:85], s[10:11]
	s_cbranch_execz .LBB0_448
	s_waitcnt lgkmcnt(8)
	v_fmamk_f32 v158, v126, 0x3e38aa3b, v251
.LBB0_448:
	s_or_b64 exec, exec, s[84:85]
	s_and_saveexec_b64 s[84:85], s[14:15]
	s_cbranch_execz .LBB0_450
	s_waitcnt lgkmcnt(8)
	v_fmamk_f32 v157, v127, 0x3e38aa3b, v252
.LBB0_450:
	s_or_b64 exec, exec, s[84:85]
	v_mov_b32_e32 v148, 0xf149f2ca
	v_mov_b32_e32 v159, 0xf149f2ca
	s_and_saveexec_b64 s[84:85], s[16:17]
	s_cbranch_execz .LBB0_452
	s_waitcnt lgkmcnt(8)
	v_fmamk_f32 v159, v128, 0x3e38aa3b, v253
.LBB0_452:
	s_or_b64 exec, exec, s[84:85]
	s_and_saveexec_b64 s[84:85], s[18:19]
	s_cbranch_execz .LBB0_454
	s_waitcnt lgkmcnt(8)
	v_fmamk_f32 v148, v129, 0x3e38aa3b, v254
.LBB0_454:
	s_or_b64 exec, exec, s[84:85]
	s_waitcnt lgkmcnt(0)
	ds_read_b32 v247, v231 offset:1796
	ds_read_b32 v248, v231 offset:1800
	ds_read_b32 v249, v231 offset:1804
	ds_read_b32 v250, v231 offset:1808
	ds_read_b32 v251, v231 offset:1860
	ds_read_b32 v252, v231 offset:1864
	ds_read_b32 v253, v231 offset:1868
	ds_read_b32 v254, v231 offset:1872
	v_mov_b32_e32 v146, 0xf149f2ca
	v_mov_b32_e32 v150, 0xf149f2ca
	s_and_saveexec_b64 s[84:85], s[0:1]
	s_cbranch_execz .LBB0_456
	s_waitcnt lgkmcnt(8)
	v_fmamk_f32 v150, v122, 0x3e38aa3b, v239
.LBB0_456:
	s_or_b64 exec, exec, s[84:85]
	s_and_saveexec_b64 s[84:85], s[4:5]
	s_cbranch_execz .LBB0_458
	s_waitcnt lgkmcnt(8)
	v_fmamk_f32 v146, v123, 0x3e38aa3b, v240
.LBB0_458:
	s_or_b64 exec, exec, s[84:85]
	v_mov_b32_e32 v140, 0xf149f2ca
	v_mov_b32_e32 v142, 0xf149f2ca
	s_and_saveexec_b64 s[84:85], s[6:7]
	s_cbranch_execz .LBB0_460
	s_waitcnt lgkmcnt(8)
	v_fmamk_f32 v142, v124, 0x3e38aa3b, v241
.LBB0_460:
	s_or_b64 exec, exec, s[84:85]
	s_and_saveexec_b64 s[84:85], s[8:9]
	s_cbranch_execz .LBB0_462
	s_waitcnt lgkmcnt(8)
	v_fmamk_f32 v140, v125, 0x3e38aa3b, v242
.LBB0_462:
	s_or_b64 exec, exec, s[84:85]
	v_mov_b32_e32 v136, 0xf149f2ca
	v_mov_b32_e32 v147, 0xf149f2ca
	s_and_saveexec_b64 s[84:85], s[10:11]
	s_cbranch_execz .LBB0_464
	s_waitcnt lgkmcnt(8)
	v_fmamk_f32 v147, v118, 0x3e38aa3b, v243
.LBB0_464:
	s_or_b64 exec, exec, s[84:85]
	s_and_saveexec_b64 s[84:85], s[14:15]
	s_cbranch_execz .LBB0_466
	s_waitcnt lgkmcnt(8)
	v_fmamk_f32 v136, v119, 0x3e38aa3b, v244
.LBB0_466:
	s_or_b64 exec, exec, s[84:85]
	v_mov_b32_e32 v131, 0xf149f2ca
	v_mov_b32_e32 v141, 0xf149f2ca
	s_and_saveexec_b64 s[84:85], s[16:17]
	s_cbranch_execz .LBB0_468
	s_waitcnt lgkmcnt(8)
	v_fmamk_f32 v141, v120, 0x3e38aa3b, v245
.LBB0_468:
	s_or_b64 exec, exec, s[84:85]
	s_and_saveexec_b64 s[84:85], s[18:19]
	s_cbranch_execz .LBB0_470
	s_waitcnt lgkmcnt(8)
	v_fmamk_f32 v131, v121, 0x3e38aa3b, v246
.LBB0_470:
	s_or_b64 exec, exec, s[84:85]
	v_mov_b32_e32 v128, 0xf149f2ca
	v_mov_b32_e32 v137, 0xf149f2ca
	s_and_saveexec_b64 s[84:85], s[0:1]
	s_cbranch_execz .LBB0_472
	s_waitcnt lgkmcnt(0)
	v_fmamk_f32 v137, v114, 0x3e38aa3b, v247
.LBB0_472:
	s_or_b64 exec, exec, s[84:85]
	s_and_saveexec_b64 s[0:1], s[4:5]
	s_cbranch_execz .LBB0_474
	s_waitcnt lgkmcnt(0)
	v_fmamk_f32 v128, v115, 0x3e38aa3b, v248
.LBB0_474:
	s_or_b64 exec, exec, s[0:1]
	v_mov_b32_e32 v132, 0xf149f2ca
	v_mov_b32_e32 v133, 0xf149f2ca
	s_and_saveexec_b64 s[0:1], s[6:7]
	s_cbranch_execz .LBB0_476
	s_waitcnt lgkmcnt(0)
	v_fmamk_f32 v133, v116, 0x3e38aa3b, v249
.LBB0_476:
	s_or_b64 exec, exec, s[0:1]
	s_and_saveexec_b64 s[0:1], s[8:9]
	s_cbranch_execz .LBB0_478
	s_waitcnt lgkmcnt(0)
	v_fmamk_f32 v132, v117, 0x3e38aa3b, v250
.LBB0_478:
	s_or_b64 exec, exec, s[0:1]
	v_mov_b32_e32 v129, 0xf149f2ca
	v_mov_b32_e32 v130, 0xf149f2ca
	s_and_saveexec_b64 s[0:1], s[10:11]
	s_cbranch_execz .LBB0_480
	s_waitcnt lgkmcnt(0)
	v_fmamk_f32 v130, v110, 0x3e38aa3b, v251
.LBB0_480:
	s_or_b64 exec, exec, s[0:1]
	s_and_saveexec_b64 s[0:1], s[14:15]
	s_cbranch_execz .LBB0_482
	s_waitcnt lgkmcnt(0)
	v_fmamk_f32 v129, v111, 0x3e38aa3b, v252
.LBB0_482:
	s_or_b64 exec, exec, s[0:1]
	v_mov_b32_e32 v126, 0xf149f2ca
	v_mov_b32_e32 v127, 0xf149f2ca
	s_and_saveexec_b64 s[0:1], s[16:17]
	s_cbranch_execz .LBB0_484
	s_waitcnt lgkmcnt(0)
	v_fmamk_f32 v127, v112, 0x3e38aa3b, v253
.LBB0_484:
	s_or_b64 exec, exec, s[0:1]
	s_and_saveexec_b64 s[0:1], s[18:19]
	s_cbranch_execz .LBB0_352
	s_waitcnt lgkmcnt(0)
	v_fmamk_f32 v126, v113, 0x3e38aa3b, v254
	s_branch .LBB0_352

; __device__ __forceinline__ void mixC_mfma(const bf16* P, const float* rpb  , bf16* MIX, LAS unsigned char* lds, int bid, int G, int tid) {
;     ...
;             for (int t = 0; t < 4; ++t) {
;                 const bool ok = (unsigned)(d0 + 16 * (kt & 1) + t) < 16u;
;                 const float sv = ok ? S[kt][t] * (0.125f * L2E) + rpl[(kt >> 1) * 31 + 16 * (kt & 1) + t] : -1e30f;
;                 S[kt][t] = sv; mx = fmaxf(mx, sv);
.LBB0_492:
	s_waitcnt lgkmcnt(0)
	v_fmamk_f32 v139, v178, 0x3e38aa3b, v239
	s_or_b64 exec, exec, s[84:85]
	s_and_saveexec_b64 s[84:85], s[4:5]
	s_cbranch_execnz .LBB0_425
	s_branch .LBB0_426

; #define LAS __attribute__((address_space(3)))
; __device__ __forceinline__ void mixC_mfma(const bf16* P, const float* rpb  , bf16* MIX, LAS unsigned char* lds, int bid, int G, int tid) {
;     ...
;         const int r = rf + (wave >> 2), j = wave & 3;
;         int rs = r - 4; rs = rs < 0 ? 0 : rs; rs = rs > rows - 8 ? rows - 8 : rs;
;         const int kcol0 = j == 0 ? 0 : (j == 1 ? 8 : (j == 2 ? 24 : 32));
;         const int c = 16 * j + fr; int cs = c - 8; cs = cs < 0 ? 0 : cs; cs = cs > 48 ? 48 : cs;
;         const size_t qrow = (size_t)(s0 + r * 64 + c);
;         f32x4 S[16];
;         bf16x8 Kl[8][2];
; #pragma unroll
;         for (int kt = 8; kt < 16; ++kt) { const bf16* kp = P + (size_t)(s0 + (rs + (kt >> 1)) * 64 + kcol0 + 16 * (kt & 1) + fr) * DIN + C_KC + h * 64 + fq * 8;
;             Kl[kt - 8][0] = *(const bf16x8*)kp; Kl[kt - 8][1] = *(const bf16x8*)(kp + 32); }
; #pragma unroll
;         for (int kt = 0; kt < 8; ++kt) { f32x4 z = {0.f, 0.f, 0.f, 0.f};
;             z = __builtin_amdgcn_mfma_f32_16x16x32_bf16(Kn[kt][0], Qn0, z, 0, 0, 0);
;             S[kt] = __builtin_amdgcn_mfma_f32_16x16x32_bf16(Kn[kt][1], Qn1, z, 0, 0, 0); }
;         const int d0 = kcol0 + 4 * fq - cs;
;         const LAS float* rpl = rp + h * 512 + (rs - r + 7) * 31 + (kcol0 + 4 * fq - c + 15);
;         float m1 = -1e30f;
; #pragma unroll
;         for (int kt = 0; kt < 8; ++kt)
; #pragma unroll
;             for (int t = 0; t < 4; ++t) {
;                 const bool ok = (unsigned)(d0 + 16 * (kt & 1) + t) < 16u;
;                 const float sv = ok ? S[kt][t] * (0.125f * L2E) + rpl[(kt >> 1) * 31 + 16 * (kt & 1) + t] : -1e30f;
;                 S[kt][t] = sv; m1 = fmaxf(m1, sv);
;             }
.LBB0_1383:
	s_add_i32 s83, s83, s13
	s_max_i32 s0, s83, 4
	s_add_i32 s0, s0, -4
	s_min_u32 s86, s0, s5
	v_or_b32_e32 v110, s82, v213
	s_lshl_b32 s5, s86, 6
	v_add_u32_e32 v162, s85, v110
	s_add_i32 s6, s5, 0x100
	s_lshl_b32 s24, s4, 6
	v_add_u32_e32 v110, s6, v162
	v_mov_b64_e32 v[170:171], s[74:75]
	s_ashr_i32 s25, s24, 31
	v_mad_i64_i32 v[110:111], s[0:1], v110, s79, v[170:171]
	s_lshl_b64 s[0:1], s[24:25], 1
	v_add_u32_e32 v172, 16, v162
	v_lshl_add_u64 v[110:111], v[110:111], 0, s[0:1]
	v_add_u32_e32 v118, s6, v172
	v_lshl_add_u64 v[110:111], v[110:111], 0, v[210:211]
	v_mad_i64_i32 v[118:119], s[6:7], v118, s79, v[170:171]
	s_add_i32 s8, s5, 0x140
	s_waitcnt vmcnt(15)
	v_mfma_f32_16x16x32_bf16 v[142:145], v[46:49], v[38:41], 0
	v_lshl_add_u64 v[114:115], v[110:111], 0, s[20:21]
	v_add_co_u32_e32 v110, vcc, s80, v110
	v_lshl_add_u64 v[118:119], v[118:119], 0, s[0:1]
	v_add_u32_e32 v126, s8, v162
	v_addc_co_u32_e32 v111, vcc, 0, v111, vcc
	v_lshl_add_u64 v[118:119], v[118:119], 0, v[210:211]
	v_mad_i64_i32 v[126:127], s[6:7], v126, s79, v[170:171]
	v_lshl_add_u64 v[122:123], v[118:119], 0, s[20:21]
	v_add_co_u32_e32 v118, vcc, s80, v118
	v_lshl_add_u64 v[126:127], v[126:127], 0, s[0:1]
	v_add_u32_e32 v134, s8, v172
	s_add_i32 s8, s5, 0x180
	v_addc_co_u32_e32 v119, vcc, 0, v119, vcc
	v_lshl_add_u64 v[126:127], v[126:127], 0, v[210:211]
	v_mad_i64_i32 v[134:135], s[6:7], v134, s79, v[170:171]
	s_waitcnt vmcnt(14)
	v_mfma_f32_16x16x32_bf16 v[202:205], v[50:53], v[42:45], v[142:145]
	v_lshl_add_u64 v[130:131], v[126:127], 0, s[20:21]
	v_add_co_u32_e32 v126, vcc, s80, v126
	s_nop 0
	v_add_u32_e32 v142, s8, v162
	v_lshl_add_u64 v[134:135], v[134:135], 0, s[0:1]
	v_mad_i64_i32 v[146:147], s[6:7], v142, s79, v[170:171]
	s_waitcnt vmcnt(13)
	v_mfma_f32_16x16x32_bf16 v[142:145], v[54:57], v[38:41], 0
	v_addc_co_u32_e32 v127, vcc, 0, v127, vcc
	v_lshl_add_u64 v[134:135], v[134:135], 0, v[210:211]
	v_lshl_add_u64 v[136:137], v[134:135], 0, s[20:21]
	v_add_co_u32_e32 v134, vcc, s80, v134
	v_lshl_add_u64 v[146:147], v[146:147], 0, s[0:1]
	s_nop 0
	v_addc_co_u32_e32 v135, vcc, 0, v135, vcc
	v_lshl_add_u64 v[146:147], v[146:147], 0, v[210:211]
	s_waitcnt vmcnt(12)
	v_mfma_f32_16x16x32_bf16 v[198:201], v[58:61], v[42:45], v[142:145]
	v_lshl_add_u64 v[150:151], v[146:147], 0, s[20:21]
	global_load_dwordx4 v[110:113], v[110:111], off
	s_nop 0
	global_load_dwordx4 v[114:117], v[114:115], off offset:64
	v_add_co_u32_e32 v142, vcc, s80, v146
	global_load_dwordx4 v[118:121], v[118:119], off
	s_nop 0
	global_load_dwordx4 v[122:125], v[122:123], off offset:64
	v_addc_co_u32_e32 v143, vcc, 0, v147, vcc
	global_load_dwordx4 v[126:129], v[126:127], off
	s_nop 0
	global_load_dwordx4 v[130:133], v[130:131], off offset:64
	s_nop 0
	global_load_dwordx4 v[138:141], v[134:135], off
	s_nop 0
	global_load_dwordx4 v[134:137], v[136:137], off offset:64
	s_nop 0
	global_load_dwordx4 v[146:149], v[142:143], off
	s_nop 0
	global_load_dwordx4 v[142:145], v[150:151], off offset:64
	s_waitcnt vmcnt(21)
	v_mfma_f32_16x16x32_bf16 v[150:153], v[62:65], v[38:41], 0
	v_add_u32_e32 v154, s8, v172
	v_mad_i64_i32 v[154:155], s[6:7], v154, s79, v[170:171]
	s_waitcnt vmcnt(20)
	v_mfma_f32_16x16x32_bf16 v[194:197], v[66:69], v[42:45], v[150:153]
	s_addk_i32 s5, 0x1c0
	v_add_u32_e32 v162, s5, v162
	v_mad_i64_i32 v[162:163], s[6:7], v162, s79, v[170:171]
	s_nop 0
	v_lshl_add_u64 v[150:151], v[154:155], 0, s[0:1]
	v_lshl_add_u64 v[154:155], v[150:151], 0, v[210:211]
	s_waitcnt vmcnt(19)
	v_mfma_f32_16x16x32_bf16 v[150:153], v[70:73], v[38:41], 0
	v_lshl_add_u64 v[158:159], v[154:155], 0, s[20:21]
	v_add_co_u32_e32 v154, vcc, s80, v154
	s_waitcnt vmcnt(15)
	v_mfma_f32_16x16x32_bf16 v[166:169], v[86:89], v[38:41], 0
	v_addc_co_u32_e32 v155, vcc, 0, v155, vcc
	v_add_u32_e32 v217, s85, v212
	v_mfma_f32_16x16x32_bf16 v[190:193], v[74:77], v[42:45], v[150:153]
	global_load_dwordx4 v[154:157], v[154:155], off
	s_nop 1
	global_load_dwordx4 v[150:153], v[158:159], off offset:64
	v_sub_u32_e32 v215, v217, v209
	v_sub_u32_e32 v217, v217, v1
	v_mfma_f32_16x16x32_bf16 v[158:161], v[82:85], v[38:41], 0
	s_waitcnt vmcnt(16)
	v_mfma_f32_16x16x32_bf16 v[182:185], v[90:93], v[42:45], v[166:169]
	s_nop 2
	v_add_u32_e32 v166, s5, v172
	v_mfma_f32_16x16x32_bf16 v[186:189], v[78:81], v[42:45], v[158:161]
	v_mad_i64_i32 v[170:171], s[6:7], v166, s79, v[170:171]
	v_lshl_add_u64 v[170:171], v[170:171], 0, s[0:1]
	s_nop 0
	v_lshl_add_u64 v[158:159], v[162:163], 0, s[0:1]
	s_waitcnt vmcnt(15)
	v_mfma_f32_16x16x32_bf16 v[166:169], v[94:97], v[38:41], 0
	v_lshl_add_u64 v[158:159], v[158:159], 0, v[210:211]
	v_lshl_add_u64 v[160:161], v[158:159], 0, s[20:21]
	v_add_co_u32_e32 v158, vcc, s80, v158
	v_lshl_add_u64 v[170:171], v[170:171], 0, v[210:211]
	s_nop 0
	v_addc_co_u32_e32 v159, vcc, 0, v159, vcc
	s_waitcnt vmcnt(14)
	v_mfma_f32_16x16x32_bf16 v[178:181], v[98:101], v[42:45], v[166:169]
	global_load_dwordx4 v[162:165], v[158:159], off
	s_nop 0
	global_load_dwordx4 v[158:161], v[160:161], off offset:64
	v_add_co_u32_e32 v166, vcc, s80, v170
	v_lshl_add_u64 v[230:231], v[170:171], 0, s[20:21]
	s_nop 0
	v_addc_co_u32_e32 v167, vcc, 0, v171, vcc
	global_load_dwordx4 v[170:173], v[166:167], off
	s_nop 0
	global_load_dwordx4 v[166:169], v[230:231], off offset:64
	s_waitcnt vmcnt(17)
	v_mfma_f32_16x16x32_bf16 v[174:177], v[102:105], v[38:41], 0
	s_lshl_b32 s0, s4, 11
	s_sub_i32 s1, s86, s83
	s_add_i32 s0, s0, 0
	s_waitcnt vmcnt(16)
	v_mfma_f32_16x16x32_bf16 v[174:177], v[106:109], v[42:45], v[174:177]
	s_mulk_i32 s1, 0x7c
	s_add_i32 s0, s0, s1
	v_add_u32_e32 v230, 8, v215
	s_add_i32 s0, s0, 0x16800
	v_lshl_add_u32 v231, v217, 2, s0
	ds_read_b32 v46, v231 offset:928
	ds_read_b32 v47, v231 offset:932
	ds_read_b32 v48, v231 offset:936
	ds_read_b32 v49, v231 offset:940
	ds_read_b32 v50, v231 offset:992
	ds_read_b32 v51, v231 offset:996
	ds_read_b32 v52, v231 offset:1000
	ds_read_b32 v53, v231 offset:1004
	ds_read_b32 v54, v231 offset:1052
	ds_read_b32 v55, v231 offset:1056
	ds_read_b32 v56, v231 offset:1060
	ds_read_b32 v57, v231 offset:1064
	ds_read_b32 v58, v231 offset:1116
	ds_read_b32 v59, v231 offset:1120
	ds_read_b32 v60, v231 offset:1124
	ds_read_b32 v61, v231 offset:1128
	v_cmp_gt_u32_e64 s[0:1], 16, v230
	v_mov_b32_e32 v217, 0xf149f2ca
	v_mov_b32_e32 v230, 0xf149f2ca
	s_and_saveexec_b64 s[4:5], s[0:1]
	s_cbranch_execz .LBB0_1385
	s_waitcnt lgkmcnt(0)
	v_fmamk_f32 v230, v202, 0x3e38aa3b, v46

; __device__ __forceinline__ void mixC_mfma(const bf16* P, const float* rpb  , bf16* MIX, LAS unsigned char* lds, int bid, int G, int tid) {
;     ...
; #pragma unroll
;         for (int kt = 0; kt < 8; ++kt)
; #pragma unroll
;             for (int t = 0; t < 4; ++t) {
;                 const bool ok = (unsigned)(d0 + 16 * (kt & 1) + t) < 16u;
;                 const float sv = ok ? S[kt][t] * (0.125f * L2E) + rpl[(kt >> 1) * 31 + 16 * (kt & 1) + t] : -1e30f;
;                 S[kt][t] = sv; m1 = fmaxf(m1, sv);
;             }
.LBB0_1397:
	s_or_b64 exec, exec, s[18:19]
	v_add_u32_e32 v200, 27, v215
	v_cmp_gt_u32_e64 s[18:19], 16, v200
	s_and_saveexec_b64 s[26:27], s[18:19]
	s_cbranch_execz .LBB0_1399
	s_waitcnt lgkmcnt(0)
	v_fmamk_f32 v198, v201, 0x3e38aa3b, v53
.LBB0_1399:
	s_or_b64 exec, exec, s[26:27]
	s_waitcnt lgkmcnt(0)
	ds_read_b32 v46, v231 offset:1176
	ds_read_b32 v47, v231 offset:1180
	ds_read_b32 v48, v231 offset:1184
	ds_read_b32 v49, v231 offset:1188
	ds_read_b32 v50, v231 offset:1240
	ds_read_b32 v51, v231 offset:1244
	ds_read_b32 v52, v231 offset:1248
	ds_read_b32 v53, v231 offset:1252
	v_mov_b32_e32 v200, 0xf149f2ca
	v_mov_b32_e32 v201, 0xf149f2ca
	s_and_saveexec_b64 s[26:27], s[0:1]
	s_cbranch_execz .LBB0_1401
	s_waitcnt lgkmcnt(8)
	v_fmamk_f32 v201, v194, 0x3e38aa3b, v54
.LBB0_1401:
	s_or_b64 exec, exec, s[26:27]
	s_and_saveexec_b64 s[26:27], s[4:5]
	s_cbranch_execz .LBB0_1403
	s_waitcnt lgkmcnt(8)
	v_fmamk_f32 v200, v195, 0x3e38aa3b, v55
.LBB0_1403:
	s_or_b64 exec, exec, s[26:27]
	v_mov_b32_e32 v194, 0xf149f2ca
	v_mov_b32_e32 v195, 0xf149f2ca
	s_and_saveexec_b64 s[26:27], s[6:7]
	s_cbranch_execz .LBB0_1405
	s_waitcnt lgkmcnt(8)
	v_fmamk_f32 v195, v196, 0x3e38aa3b, v56
.LBB0_1405:
	s_or_b64 exec, exec, s[26:27]
	s_and_saveexec_b64 s[26:27], s[8:9]
	s_cbranch_execz .LBB0_1407
	s_waitcnt lgkmcnt(8)
	v_fmamk_f32 v194, v197, 0x3e38aa3b, v57
.LBB0_1407:
	s_or_b64 exec, exec, s[26:27]
	v_mov_b32_e32 v196, 0xf149f2ca
	v_mov_b32_e32 v197, 0xf149f2ca
	s_and_saveexec_b64 s[26:27], s[10:11]
	s_cbranch_execz .LBB0_1409
	s_waitcnt lgkmcnt(8)
	v_fmamk_f32 v197, v190, 0x3e38aa3b, v58
.LBB0_1409:
	s_or_b64 exec, exec, s[26:27]
	s_and_saveexec_b64 s[26:27], s[14:15]
	s_cbranch_execz .LBB0_1411
	s_waitcnt lgkmcnt(8)
	v_fmamk_f32 v196, v191, 0x3e38aa3b, v59
.LBB0_1411:
	s_or_b64 exec, exec, s[26:27]
	v_mov_b32_e32 v190, 0xf149f2ca
	v_mov_b32_e32 v191, 0xf149f2ca
	s_and_saveexec_b64 s[26:27], s[16:17]
	s_cbranch_execz .LBB0_1413
	s_waitcnt lgkmcnt(8)
	v_fmamk_f32 v191, v192, 0x3e38aa3b, v60
.LBB0_1413:
	s_or_b64 exec, exec, s[26:27]
	s_and_saveexec_b64 s[26:27], s[18:19]
	s_cbranch_execz .LBB0_1415
	s_waitcnt lgkmcnt(8)
	v_fmamk_f32 v190, v193, 0x3e38aa3b, v61
.LBB0_1415:
	s_or_b64 exec, exec, s[26:27]
	s_waitcnt lgkmcnt(0)
	ds_read_b32 v54, v231 offset:1300
	ds_read_b32 v55, v231 offset:1304
	ds_read_b32 v56, v231 offset:1308
	ds_read_b32 v57, v231 offset:1312
	ds_read_b32 v58, v231 offset:1364
	ds_read_b32 v59, v231 offset:1368
	ds_read_b32 v60, v231 offset:1372
	ds_read_b32 v61, v231 offset:1376
	v_mov_b32_e32 v192, 0xf149f2ca
	v_mov_b32_e32 v193, 0xf149f2ca
	s_and_saveexec_b64 s[26:27], s[0:1]
	s_cbranch_execz .LBB0_1417
	s_waitcnt lgkmcnt(8)
	v_fmamk_f32 v193, v186, 0x3e38aa3b, v46
.LBB0_1417:
	s_or_b64 exec, exec, s[26:27]
	s_and_saveexec_b64 s[26:27], s[4:5]
	s_cbranch_execz .LBB0_1419
	s_waitcnt lgkmcnt(8)
	v_fmamk_f32 v192, v187, 0x3e38aa3b, v47
.LBB0_1419:
	s_or_b64 exec, exec, s[26:27]
	v_mov_b32_e32 v186, 0xf149f2ca
	v_mov_b32_e32 v187, 0xf149f2ca
	s_and_saveexec_b64 s[26:27], s[6:7]
	s_cbranch_execz .LBB0_1421
	s_waitcnt lgkmcnt(8)
	v_fmamk_f32 v187, v188, 0x3e38aa3b, v48
.LBB0_1421:
	s_or_b64 exec, exec, s[26:27]
	s_and_saveexec_b64 s[26:27], s[8:9]
	s_cbranch_execz .LBB0_1423
	s_waitcnt lgkmcnt(8)
	v_fmamk_f32 v186, v189, 0x3e38aa3b, v49
.LBB0_1423:
	s_or_b64 exec, exec, s[26:27]
	v_mov_b32_e32 v188, 0xf149f2ca
	v_mov_b32_e32 v189, 0xf149f2ca
	s_and_saveexec_b64 s[26:27], s[10:11]
	s_cbranch_execz .LBB0_1425
	s_waitcnt lgkmcnt(8)
	v_fmamk_f32 v189, v182, 0x3e38aa3b, v50
.LBB0_1425:
	s_or_b64 exec, exec, s[26:27]
	s_and_saveexec_b64 s[26:27], s[14:15]
	s_cbranch_execz .LBB0_1427
	s_waitcnt lgkmcnt(8)
	v_fmamk_f32 v188, v183, 0x3e38aa3b, v51
.LBB0_1427:
	s_or_b64 exec, exec, s[26:27]
	v_mov_b32_e32 v182, 0xf149f2ca
	v_mov_b32_e32 v183, 0xf149f2ca
	s_and_saveexec_b64 s[26:27], s[16:17]
	s_cbranch_execz .LBB0_1429
	s_waitcnt lgkmcnt(8)
	v_fmamk_f32 v183, v184, 0x3e38aa3b, v52
.LBB0_1429:
	s_or_b64 exec, exec, s[26:27]
	s_and_saveexec_b64 s[26:27], s[18:19]
	s_cbranch_execz .LBB0_1431
	s_waitcnt lgkmcnt(8)
	v_fmamk_f32 v182, v185, 0x3e38aa3b, v53
.LBB0_1431:
	s_or_b64 exec, exec, s[26:27]
	v_mov_b32_e32 v184, 0xf149f2ca
	v_mov_b32_e32 v185, 0xf149f2ca
	s_and_saveexec_b64 s[26:27], s[0:1]
	s_cbranch_execz .LBB0_1433
	s_waitcnt lgkmcnt(0)
	v_fmamk_f32 v185, v178, 0x3e38aa3b, v54
; __device__ __forceinline__ void mixC_mfma(const bf16* P, const float* rpb  , bf16* MIX, LAS unsigned char* lds, int bid, int G, int tid) {
;     ...
;                 const bool ok = (unsigned)(d0 + 16 * (kt & 1) + t) < 16u;
;                 const float sv = ok ? S[kt][t] * (0.125f * L2E) + rpl[(kt >> 1) * 31 + 16 * (kt & 1) + t] : -1e30f;
;                 S[kt][t] = sv; m1 = fmaxf(m1, sv);
;             }
;         m1 = fmaxf(m1, __shfl_xor(m1, 16)); m1 = fmaxf(m1, __shfl_xor(m1, 32));
;         float l1 = 0.f;
; #pragma unroll
;         for (int kt = 0; kt < 8; ++kt)
; #pragma unroll
;             for (int t = 0; t < 4; ++t) { const float p = __builtin_amdgcn_exp2f(S[kt][t] - m1); S[kt][t] = p; l1 += p; }
; #pragma unroll
;         for (int kt = 8; kt < 16; ++kt) { f32x4 z = {0.f, 0.f, 0.f, 0.f};
;             z = __builtin_amdgcn_mfma_f32_16x16x32_bf16(Kl[kt - 8][0], Qn0, z, 0, 0, 0);
;             S[kt] = __builtin_amdgcn_mfma_f32_16x16x32_bf16(Kl[kt - 8][1], Qn1, z, 0, 0, 0); }
;         asm volatile("" ::: "memory");
;         if (un + G < NU) c_prefetch(P, un + G, tid, wave, fr, fq, vpre, Qn0, Qn1, Kn);
.LBB0_1433:
	s_or_b64 exec, exec, s[26:27]
	s_and_saveexec_b64 s[26:27], s[4:5]
	s_cbranch_execz .LBB0_1435
	s_waitcnt lgkmcnt(0)
	v_fmamk_f32 v184, v179, 0x3e38aa3b, v55
.LBB0_1435:
	s_or_b64 exec, exec, s[26:27]
	v_mov_b32_e32 v232, 0xf149f2ca
	v_mov_b32_e32 v233, 0xf149f2ca
	s_and_saveexec_b64 s[26:27], s[6:7]
	s_cbranch_execz .LBB0_1437
	s_waitcnt lgkmcnt(0)
	v_fmamk_f32 v233, v180, 0x3e38aa3b, v56
.LBB0_1437:
	s_or_b64 exec, exec, s[26:27]
	s_and_saveexec_b64 s[26:27], s[8:9]
	s_cbranch_execz .LBB0_1439
	s_waitcnt lgkmcnt(0)
	v_fmamk_f32 v232, v181, 0x3e38aa3b, v57
.LBB0_1439:
	s_or_b64 exec, exec, s[26:27]
	v_mov_b32_e32 v234, 0xf149f2ca
	v_mov_b32_e32 v235, 0xf149f2ca
	s_and_saveexec_b64 s[26:27], s[10:11]
	s_cbranch_execz .LBB0_1441
	s_waitcnt lgkmcnt(0)
	v_fmamk_f32 v235, v174, 0x3e38aa3b, v58
.LBB0_1441:
	s_or_b64 exec, exec, s[26:27]
	s_and_saveexec_b64 s[26:27], s[14:15]
	s_cbranch_execz .LBB0_1443
	s_waitcnt lgkmcnt(0)
	v_fmamk_f32 v234, v175, 0x3e38aa3b, v59
.LBB0_1443:
	s_or_b64 exec, exec, s[26:27]
	v_mov_b32_e32 v236, 0xf149f2ca
	v_mov_b32_e32 v237, 0xf149f2ca
	s_and_saveexec_b64 s[26:27], s[16:17]
	s_cbranch_execz .LBB0_1445
	s_waitcnt lgkmcnt(0)
	v_fmamk_f32 v237, v176, 0x3e38aa3b, v60
.LBB0_1445:
	s_or_b64 exec, exec, s[26:27]
	s_and_saveexec_b64 s[26:27], s[18:19]
	s_cbranch_execz .LBB0_1447
	s_waitcnt lgkmcnt(0)
	v_fmamk_f32 v236, v177, 0x3e38aa3b, v61
.LBB0_1447:
	s_or_b64 exec, exec, s[26:27]
	s_waitcnt vmcnt(15)
	v_mfma_f32_16x16x32_bf16 v[110:113], v[110:113], v[38:41], 0
	s_mov_b32 s26, 0xf149f2ca
	s_add_i32 s12, s12, s68
	s_waitcnt vmcnt(14)
	v_mfma_f32_16x16x32_bf16 v[178:181], v[114:117], v[42:45], v[110:113]
	v_max3_f32 v114, v230, s26, v217
	s_cmpk_gt_i32 s12, 0x8ff
	s_cselect_b64 s[26:27], -1, 0
	s_waitcnt vmcnt(13)
	v_mfma_f32_16x16x32_bf16 v[110:113], v[118:121], v[38:41], 0
	s_and_b64 vcc, exec, s[26:27]
	s_waitcnt vmcnt(12)
	v_mfma_f32_16x16x32_bf16 v[174:177], v[122:125], v[42:45], v[110:113]
	s_waitcnt vmcnt(11)
	v_mfma_f32_16x16x32_bf16 v[110:113], v[126:129], v[38:41], 0
	s_waitcnt vmcnt(10)
	v_mfma_f32_16x16x32_bf16 v[130:133], v[130:133], v[42:45], v[110:113]
	s_waitcnt vmcnt(9)
	v_mfma_f32_16x16x32_bf16 v[110:113], v[138:141], v[38:41], 0
	s_waitcnt vmcnt(8)
	v_mfma_f32_16x16x32_bf16 v[126:129], v[134:137], v[42:45], v[110:113]
	s_nop 5
	v_max3_f32 v110, v114, v203, v202
	v_max3_f32 v110, v110, v205, v204
	v_max3_f32 v114, v110, v199, v198
	s_waitcnt vmcnt(7)
	v_mfma_f32_16x16x32_bf16 v[110:113], v[146:149], v[38:41], 0
	v_max3_f32 v114, v114, v201, v200
	v_max3_f32 v114, v114, v195, v194
	v_max3_f32 v114, v114, v197, v196
	s_waitcnt vmcnt(6)
	v_mfma_f32_16x16x32_bf16 v[122:125], v[142:145], v[42:45], v[110:113]
	s_nop 2
	v_max3_f32 v110, v114, v191, v190
	v_max3_f32 v110, v110, v193, v192
	v_max3_f32 v114, v110, v187, v186
	s_waitcnt vmcnt(5)
	v_mfma_f32_16x16x32_bf16 v[110:113], v[154:157], v[38:41], 0
	v_max3_f32 v114, v114, v189, v188
	v_max3_f32 v114, v114, v183, v182
	v_max3_f32 v114, v114, v185, v184
	s_waitcnt vmcnt(4)
	v_mfma_f32_16x16x32_bf16 v[118:121], v[150:153], v[42:45], v[110:113]
	s_nop 2
	v_max3_f32 v110, v114, v233, v232
	v_max3_f32 v110, v110, v235, v234
	v_max3_f32 v114, v110, v237, v236
	ds_bpermute_b32 v115, v219, v114
	s_waitcnt vmcnt(3)
	v_mfma_f32_16x16x32_bf16 v[110:113], v[162:165], v[38:41], 0
	s_waitcnt lgkmcnt(0)
	v_max_f32_e32 v115, v115, v115
	v_max_f32_e32 v134, v114, v115
	s_waitcnt vmcnt(2)
	v_mfma_f32_16x16x32_bf16 v[114:117], v[158:161], v[42:45], v[110:113]
	ds_bpermute_b32 v135, v220, v134
	s_waitcnt vmcnt(1)
	v_mfma_f32_16x16x32_bf16 v[110:113], v[170:173], v[38:41], 0
	s_waitcnt vmcnt(0)
	v_mfma_f32_16x16x32_bf16 v[110:113], v[166:169], v[42:45], v[110:113]
	ds_read_b32 v239, v231 offset:1424
	ds_read_b32 v240, v231 offset:1428
	ds_read_b32 v241, v231 offset:1432
	ds_read_b32 v242, v231 offset:1436
	ds_read_b32 v243, v231 offset:1488
	ds_read_b32 v244, v231 offset:1492
	ds_read_b32 v245, v231 offset:1496
	ds_read_b32 v246, v231 offset:1500
	ds_read_b32 v247, v231 offset:1548
	ds_read_b32 v248, v231 offset:1552
	ds_read_b32 v249, v231 offset:1556
	ds_read_b32 v250, v231 offset:1560
	ds_read_b32 v251, v231 offset:1612
	ds_read_b32 v252, v231 offset:1616
	ds_read_b32 v253, v231 offset:1620
	ds_read_b32 v254, v231 offset:1624
	s_cbranch_vccz .LBB0_1511
	v_mov_b32_e32 v138, 0xf149f2ca
	v_mov_b32_e32 v139, 0xf149f2ca
	s_and_saveexec_b64 s[40:41], s[0:1]
	s_cbranch_execnz .LBB0_1517

; __device__ __forceinline__ void mixC_mfma(const bf16* P, const float* rpb  , bf16* MIX, LAS unsigned char* lds, int bid, int G, int tid) {
;     ...
; #pragma unroll
;         for (int kt = 8; kt < 16; ++kt)
; #pragma unroll
;             for (int t = 0; t < 4; ++t) {
;                 const bool ok = (unsigned)(d0 + 16 * (kt & 1) + t) < 16u;
;                 const float sv = ok ? S[kt][t] * (0.125f * L2E) + rpl[(kt >> 1) * 31 + 16 * (kt & 1) + t] : -1e30f;
;                 S[kt][t] = sv; mx = fmaxf(mx, sv);
;             }
.LBB0_1451:
	s_or_b64 exec, exec, s[40:41]
	v_mov_b32_e32 v143, 0xf149f2ca
	v_mov_b32_e32 v144, 0xf149f2ca
	s_and_saveexec_b64 s[40:41], s[6:7]
	s_cbranch_execz .LBB0_1453
	s_waitcnt lgkmcnt(0)
	v_fmamk_f32 v144, v180, 0x3e38aa3b, v241
.LBB0_1453:
	s_or_b64 exec, exec, s[40:41]
	s_and_saveexec_b64 s[40:41], s[8:9]
	s_cbranch_execz .LBB0_1455
	s_waitcnt lgkmcnt(0)
	v_fmamk_f32 v143, v181, 0x3e38aa3b, v242
.LBB0_1455:
	s_or_b64 exec, exec, s[40:41]
	v_mov_b32_e32 v145, 0xf149f2ca
	v_mov_b32_e32 v149, 0xf149f2ca
	s_and_saveexec_b64 s[40:41], s[10:11]
	s_cbranch_execz .LBB0_1457
	s_waitcnt lgkmcnt(0)
	v_fmamk_f32 v149, v174, 0x3e38aa3b, v243
.LBB0_1457:
	s_or_b64 exec, exec, s[40:41]
	s_and_saveexec_b64 s[40:41], s[14:15]
	s_cbranch_execz .LBB0_1459
	s_waitcnt lgkmcnt(0)
	v_fmamk_f32 v145, v175, 0x3e38aa3b, v244
.LBB0_1459:
	s_or_b64 exec, exec, s[40:41]
	v_mov_b32_e32 v151, 0xf149f2ca
	v_mov_b32_e32 v152, 0xf149f2ca
	s_and_saveexec_b64 s[40:41], s[16:17]
	s_cbranch_execz .LBB0_1461
	s_waitcnt lgkmcnt(0)
	v_fmamk_f32 v152, v176, 0x3e38aa3b, v245
.LBB0_1461:
	s_or_b64 exec, exec, s[40:41]
	s_and_saveexec_b64 s[40:41], s[18:19]
	s_cbranch_execz .LBB0_1463
	s_waitcnt lgkmcnt(0)
	v_fmamk_f32 v151, v177, 0x3e38aa3b, v246
.LBB0_1463:
	s_or_b64 exec, exec, s[40:41]
	s_waitcnt lgkmcnt(0)
	ds_read_b32 v239, v231 offset:1672
	ds_read_b32 v240, v231 offset:1676
	ds_read_b32 v241, v231 offset:1680
	ds_read_b32 v242, v231 offset:1684
	ds_read_b32 v243, v231 offset:1736
	ds_read_b32 v244, v231 offset:1740
	ds_read_b32 v245, v231 offset:1744
	ds_read_b32 v246, v231 offset:1748
	v_mov_b32_e32 v153, 0xf149f2ca
	v_mov_b32_e32 v154, 0xf149f2ca
	s_and_saveexec_b64 s[40:41], s[0:1]
	s_cbranch_execz .LBB0_1465
	s_waitcnt lgkmcnt(8)
	v_fmamk_f32 v154, v130, 0x3e38aa3b, v247
.LBB0_1465:
	s_or_b64 exec, exec, s[40:41]
	s_and_saveexec_b64 s[40:41], s[4:5]
	s_cbranch_execz .LBB0_1467
	s_waitcnt lgkmcnt(8)
	v_fmamk_f32 v153, v131, 0x3e38aa3b, v248
.LBB0_1467:
	s_or_b64 exec, exec, s[40:41]
	v_mov_b32_e32 v155, 0xf149f2ca
	v_mov_b32_e32 v156, 0xf149f2ca
	s_and_saveexec_b64 s[40:41], s[6:7]
	s_cbranch_execz .LBB0_1469
	s_waitcnt lgkmcnt(8)
	v_fmamk_f32 v156, v132, 0x3e38aa3b, v249
.LBB0_1469:
	s_or_b64 exec, exec, s[40:41]
	s_and_saveexec_b64 s[40:41], s[8:9]
	s_cbranch_execz .LBB0_1471
	s_waitcnt lgkmcnt(8)
	v_fmamk_f32 v155, v133, 0x3e38aa3b, v250
.LBB0_1471:
	s_or_b64 exec, exec, s[40:41]
	v_mov_b32_e32 v157, 0xf149f2ca
	v_mov_b32_e32 v158, 0xf149f2ca
	s_and_saveexec_b64 s[40:41], s[10:11]
	s_cbranch_execz .LBB0_1473
	s_waitcnt lgkmcnt(8)
	v_fmamk_f32 v158, v126, 0x3e38aa3b, v251
.LBB0_1473:
	s_or_b64 exec, exec, s[40:41]
	s_and_saveexec_b64 s[40:41], s[14:15]
	s_cbranch_execz .LBB0_1475
	s_waitcnt lgkmcnt(8)
	v_fmamk_f32 v157, v127, 0x3e38aa3b, v252
.LBB0_1475:
	s_or_b64 exec, exec, s[40:41]
	v_mov_b32_e32 v148, 0xf149f2ca
	v_mov_b32_e32 v159, 0xf149f2ca
	s_and_saveexec_b64 s[40:41], s[16:17]
	s_cbranch_execz .LBB0_1477
	s_waitcnt lgkmcnt(8)
	v_fmamk_f32 v159, v128, 0x3e38aa3b, v253
.LBB0_1477:
	s_or_b64 exec, exec, s[40:41]
	s_and_saveexec_b64 s[40:41], s[18:19]
	s_cbranch_execz .LBB0_1479
	s_waitcnt lgkmcnt(8)
	v_fmamk_f32 v148, v129, 0x3e38aa3b, v254
.LBB0_1479:
	s_or_b64 exec, exec, s[40:41]
	s_waitcnt lgkmcnt(0)
	ds_read_b32 v247, v231 offset:1796
	ds_read_b32 v248, v231 offset:1800
	ds_read_b32 v249, v231 offset:1804
	ds_read_b32 v250, v231 offset:1808
	ds_read_b32 v251, v231 offset:1860
	ds_read_b32 v252, v231 offset:1864
	ds_read_b32 v253, v231 offset:1868
	ds_read_b32 v254, v231 offset:1872
	v_mov_b32_e32 v146, 0xf149f2ca
	v_mov_b32_e32 v150, 0xf149f2ca
	s_and_saveexec_b64 s[40:41], s[0:1]
	s_cbranch_execz .LBB0_1481
	s_waitcnt lgkmcnt(8)
	v_fmamk_f32 v150, v122, 0x3e38aa3b, v239
.LBB0_1481:
	s_or_b64 exec, exec, s[40:41]
	s_and_saveexec_b64 s[40:41], s[4:5]
	s_cbranch_execz .LBB0_1483
	s_waitcnt lgkmcnt(8)
	v_fmamk_f32 v146, v123, 0x3e38aa3b, v240
.LBB0_1483:
	s_or_b64 exec, exec, s[40:41]
	v_mov_b32_e32 v140, 0xf149f2ca
	v_mov_b32_e32 v142, 0xf149f2ca
	s_and_saveexec_b64 s[40:41], s[6:7]
	s_cbranch_execz .LBB0_1485
	s_waitcnt lgkmcnt(8)
	v_fmamk_f32 v142, v124, 0x3e38aa3b, v241
.LBB0_1485:
	s_or_b64 exec, exec, s[40:41]
	s_and_saveexec_b64 s[40:41], s[8:9]
	s_cbranch_execz .LBB0_1487
	s_waitcnt lgkmcnt(8)
	v_fmamk_f32 v140, v125, 0x3e38aa3b, v242
.LBB0_1487:
	s_or_b64 exec, exec, s[40:41]
	v_mov_b32_e32 v136, 0xf149f2ca
	v_mov_b32_e32 v147, 0xf149f2ca
	s_and_saveexec_b64 s[40:41], s[10:11]
	s_cbranch_execz .LBB0_1489
	s_waitcnt lgkmcnt(8)
	v_fmamk_f32 v147, v118, 0x3e38aa3b, v243
.LBB0_1489:
	s_or_b64 exec, exec, s[40:41]
	s_and_saveexec_b64 s[40:41], s[14:15]
	s_cbranch_execz .LBB0_1491
	s_waitcnt lgkmcnt(8)
	v_fmamk_f32 v136, v119, 0x3e38aa3b, v244
.LBB0_1491:
	s_or_b64 exec, exec, s[40:41]
	v_mov_b32_e32 v131, 0xf149f2ca
	v_mov_b32_e32 v141, 0xf149f2ca
	s_and_saveexec_b64 s[40:41], s[16:17]
	s_cbranch_execz .LBB0_1493
	s_waitcnt lgkmcnt(8)
	v_fmamk_f32 v141, v120, 0x3e38aa3b, v245
.LBB0_1493:
	s_or_b64 exec, exec, s[40:41]
	s_and_saveexec_b64 s[40:41], s[18:19]
	s_cbranch_execz .LBB0_1495
	s_waitcnt lgkmcnt(8)
	v_fmamk_f32 v131, v121, 0x3e38aa3b, v246
.LBB0_1495:
	s_or_b64 exec, exec, s[40:41]
	v_mov_b32_e32 v128, 0xf149f2ca
	v_mov_b32_e32 v137, 0xf149f2ca
	s_and_saveexec_b64 s[40:41], s[0:1]
	s_cbranch_execz .LBB0_1497
	s_waitcnt lgkmcnt(0)
	v_fmamk_f32 v137, v114, 0x3e38aa3b, v247
.LBB0_1497:
	s_or_b64 exec, exec, s[40:41]
	s_and_saveexec_b64 s[0:1], s[4:5]
	s_cbranch_execz .LBB0_1499
	s_waitcnt lgkmcnt(0)
	v_fmamk_f32 v128, v115, 0x3e38aa3b, v248

; __device__ __forceinline__ void mixC_mfma(const bf16* P, const float* rpb  , bf16* MIX, LAS unsigned char* lds, int bid, int G, int tid) {
;     ...
;             for (int t = 0; t < 4; ++t) {
;                 const bool ok = (unsigned)(d0 + 16 * (kt & 1) + t) < 16u;
;                 const float sv = ok ? S[kt][t] * (0.125f * L2E) + rpl[(kt >> 1) * 31 + 16 * (kt & 1) + t] : -1e30f;
;                 S[kt][t] = sv; mx = fmaxf(mx, sv);
.LBB0_1517:
	s_waitcnt lgkmcnt(0)
	v_fmamk_f32 v139, v178, 0x3e38aa3b, v239
	s_or_b64 exec, exec, s[40:41]
	s_and_saveexec_b64 s[40:41], s[4:5]
	s_cbranch_execnz .LBB0_1450
	s_branch .LBB0_1451

; #define LAS __attribute__((address_space(3)))
; __global__ void __launch_bounds__(NTHREADS) mega_fwd(Args args) {
;     extern __shared__ __attribute__((aligned(16))) unsigned char lds_raw[];
;     LAS unsigned char* lds = (LAS unsigned char*)lds_raw;
	.amdhsa_kernel _Z8mega_fwd4Args
		.amdhsa_group_segment_fixed_size 0
		.amdhsa_private_segment_fixed_size 0
		.amdhsa_kernarg_size 416
		.amdhsa_user_sgpr_count 2
		.amdhsa_user_sgpr_dispatch_ptr 0
		.amdhsa_user_sgpr_queue_ptr 0
		.amdhsa_user_sgpr_kernarg_segment_ptr 1
		.amdhsa_user_sgpr_dispatch_id 0
		.amdhsa_user_sgpr_kernarg_preload_length 0
		.amdhsa_user_sgpr_kernarg_preload_offset 0
		.amdhsa_user_sgpr_private_segment_size 0
		.amdhsa_uses_dynamic_stack 0
		.amdhsa_enable_private_segment 0
		.amdhsa_system_sgpr_workgroup_id_x 1
		.amdhsa_system_sgpr_workgroup_id_y 0
		.amdhsa_system_sgpr_workgroup_id_z 0
		.amdhsa_system_sgpr_workgroup_info 0
		.amdhsa_system_vgpr_workitem_id 2
		.amdhsa_next_free_vgpr 256
		.amdhsa_next_free_sgpr 98
		.amdhsa_accum_offset 256
		.amdhsa_reserve_vcc 1
		.amdhsa_float_round_mode_32 0
		.amdhsa_float_round_mode_16_64 0
		.amdhsa_float_denorm_mode_32 3
		.amdhsa_float_denorm_mode_16_64 3
		.amdhsa_dx10_clamp 1
		.amdhsa_ieee_mode 1
		.amdhsa_fp16_overflow 0
		.amdhsa_tg_split 0
		.amdhsa_exception_fp_ieee_invalid_op 0
		.amdhsa_exception_fp_denorm_src 0
		.amdhsa_exception_fp_ieee_div_zero 0
		.amdhsa_exception_fp_ieee_overflow 0
		.amdhsa_exception_fp_ieee_underflow 0
		.amdhsa_exception_fp_ieee_inexact 0
		.amdhsa_exception_int_div_zero 0
	.end_amdhsa_kernel

; #define LAS __attribute__((address_space(3)))
; __global__ void __launch_bounds__(NTHREADS) mega_fwd(Args args) {
;     extern __shared__ __attribute__((aligned(16))) unsigned char lds_raw[];
;     LAS unsigned char* lds = (LAS unsigned char*)lds_raw;
amdhsa.kernels:
  - .agpr_count:     0
    .args:
      - .offset:         0
        .size:           160
        .value_kind:     by_value
      - .offset:         160
        .size:           4
        .value_kind:     hidden_block_count_x
      - .offset:         164
        .size:           4
        .value_kind:     hidden_block_count_y
      - .offset:         168
        .size:           4
        .value_kind:     hidden_block_count_z
      - .offset:         172
        .size:           2
        .value_kind:     hidden_group_size_x
      - .offset:         174
        .size:           2
        .value_kind:     hidden_group_size_y
      - .offset:         176
        .size:           2
        .value_kind:     hidden_group_size_z
      - .offset:         178
        .size:           2
        .value_kind:     hidden_remainder_x
      - .offset:         180
        .size:           2
        .value_kind:     hidden_remainder_y
      - .offset:         182
        .size:           2
        .value_kind:     hidden_remainder_z
      - .offset:         200
        .size:           8
        .value_kind:     hidden_global_offset_x
      - .offset:         208
        .size:           8
        .value_kind:     hidden_global_offset_y
      - .offset:         216
        .size:           8
        .value_kind:     hidden_global_offset_z
      - .offset:         224
        .size:           2
        .value_kind:     hidden_grid_dims
      - .offset:         248
        .size:           8
        .value_kind:     hidden_multigrid_sync_arg
      - .offset:         280
        .size:           4
        .value_kind:     hidden_dynamic_lds_size
    .group_segment_fixed_size: 0
    .kernarg_segment_align: 8
    .kernarg_segment_size: 416
    .language:       OpenCL C
    .language_version:
      - 2
      - 0
    .max_flat_workgroup_size: 512
    .name:           _Z8mega_fwd4Args
    .private_segment_fixed_size: 0
    .sgpr_count:     104
    .sgpr_spill_count: 35
    .symbol:         _Z8mega_fwd4Args.kd
    .uniform_work_group_size: 1
    .uses_dynamic_stack: false
    .vgpr_count:     256
    .vgpr_spill_count: 0
    .wavefront_size: 64
